# grid barrier: waiting blocks poll the chip-wide generation word directly (barrier index counted in the spare static LDS word) instead of the per-XCD republished word
# speedup vs baseline: 1.0013x; 1.0013x over previous
.LBB0_88:
	s_or_b64 exec, exec, s[8:9]
	s_waitcnt lgkmcnt(0)
	s_barrier
	s_and_saveexec_b64 s[8:9], s[4:5]
	v_mov_b32_e32 v0, 12
	v_mov_b32_e32 v1, 1
	ds_add_u32 v0, v1
	s_or_b64 exec, exec, s[8:9]

.LBB0_140:
	s_or_b64 exec, exec, s[12:13]
	v_cvt_f32_u32_e32 v4, v2
	s_waitcnt vmcnt(0)
	v_readfirstlane_b32 s3, v3
	v_sub_u32_e32 v3, 0, v2
	v_rcp_iflag_f32_e32 v4, v4
	v_add_u32_e32 v5, s3, v1
	v_mul_f32_e32 v4, 0x4f7ffffe, v4
	v_cvt_u32_f32_e32 v4, v4
	v_mul_lo_u32 v1, v3, v4
	v_mul_hi_u32 v1, v4, v1
	v_add_u32_e32 v1, v4, v1
	v_mul_hi_u32 v1, v5, v1
	v_mul_lo_u32 v3, v1, v2
	v_sub_u32_e32 v3, v5, v3
	v_add_u32_e32 v4, 1, v1
	v_cmp_ge_u32_e32 vcc, v3, v2
	s_nop 1
	v_cndmask_b32_e32 v1, v1, v4, vcc
	v_sub_u32_e32 v4, v3, v2
	v_cndmask_b32_e32 v3, v3, v4, vcc
	v_add_u32_e32 v4, 1, v1
	v_cmp_ge_u32_e32 vcc, v3, v2
	v_add_u32_e32 v3, 1, v5
	s_nop 0
	v_cndmask_b32_e32 v1, v1, v4, vcc
	v_mul_lo_u32 v4, v2, v1
	v_add_u32_e32 v2, v4, v2
	v_cmp_ne_u32_e32 vcc, v3, v2
	s_and_saveexec_b64 s[10:11], vcc
	s_xor_b64 s[10:11], exec, s[10:11]
	s_cbranch_execz .LBB0_154
	s_waitcnt lgkmcnt(0)
	v_mov_b32_e32 v1, 12
	ds_read_b32 v1, v1
	v_mov_b32_e32 v0, 0x3500
	global_load_dword v0, v0, s[46:47] sc1
	s_add_u32 s14, s46, 0x3500
	s_addc_u32 s15, s47, 0
	s_waitcnt lgkmcnt(0)
	s_waitcnt vmcnt(0)
	v_cmp_eq_u32_e32 vcc, v0, v1
	s_and_saveexec_b64 s[12:13], vcc
	s_cbranch_execz .LBB0_153
	s_mov_b32 s3, 1
	s_mov_b64 s[16:17], 0
	v_mov_b32_e32 v0, 0
	s_branch .LBB0_144

.LBB0_174:
	s_or_b64 exec, exec, s[6:7]
	s_waitcnt lgkmcnt(0)
	s_barrier
	s_and_saveexec_b64 s[8:9], s[4:5]
	v_mov_b32_e32 v0, 12
	v_mov_b32_e32 v1, 1
	ds_add_u32 v0, v1
	s_or_b64 exec, exec, s[8:9]

.Lgp7_last:
	v_mfma_f32_16x16x32_bf16 v[0:3], v[128:131], v[164:167], v[0:3]
	v_mfma_f32_16x16x32_bf16 v[64:67], v[128:131], v[200:203], v[64:67]
	v_mfma_f32_16x16x32_bf16 v[4:7], v[132:135], v[164:167], v[4:7]
	v_mfma_f32_16x16x32_bf16 v[68:71], v[132:135], v[200:203], v[68:71]
	v_mfma_f32_16x16x32_bf16 v[8:11], v[136:139], v[164:167], v[8:11]
	v_mfma_f32_16x16x32_bf16 v[72:75], v[136:139], v[200:203], v[72:75]
	v_mfma_f32_16x16x32_bf16 v[12:15], v[140:143], v[164:167], v[12:15]
	v_mfma_f32_16x16x32_bf16 v[76:79], v[140:143], v[200:203], v[76:79]
	v_mfma_f32_16x16x32_bf16 v[16:19], v[128:131], v[172:175], v[16:19]
	v_mfma_f32_16x16x32_bf16 v[80:83], v[128:131], v[204:207], v[80:83]
	v_mfma_f32_16x16x32_bf16 v[20:23], v[132:135], v[172:175], v[20:23]
	v_mfma_f32_16x16x32_bf16 v[84:87], v[132:135], v[204:207], v[84:87]
	v_mfma_f32_16x16x32_bf16 v[24:27], v[136:139], v[172:175], v[24:27]
	v_mfma_f32_16x16x32_bf16 v[88:91], v[136:139], v[204:207], v[88:91]
	v_mfma_f32_16x16x32_bf16 v[28:31], v[140:143], v[172:175], v[28:31]
	v_mfma_f32_16x16x32_bf16 v[92:95], v[140:143], v[204:207], v[92:95]
	v_mfma_f32_16x16x32_bf16 v[32:35], v[128:131], v[176:179], v[32:35]
	v_mfma_f32_16x16x32_bf16 v[96:99], v[128:131], v[208:211], v[96:99]
	v_mfma_f32_16x16x32_bf16 v[36:39], v[132:135], v[176:179], v[36:39]
	v_mfma_f32_16x16x32_bf16 v[100:103], v[132:135], v[208:211], v[100:103]
	v_mfma_f32_16x16x32_bf16 v[40:43], v[136:139], v[176:179], v[40:43]
	v_mfma_f32_16x16x32_bf16 v[104:107], v[136:139], v[208:211], v[104:107]
	v_mfma_f32_16x16x32_bf16 v[44:47], v[140:143], v[176:179], v[44:47]
	v_mfma_f32_16x16x32_bf16 v[108:111], v[140:143], v[208:211], v[108:111]
	v_mfma_f32_16x16x32_bf16 v[48:51], v[128:131], v[180:183], v[48:51]
	v_mfma_f32_16x16x32_bf16 v[112:115], v[128:131], v[212:215], v[112:115]
	v_mfma_f32_16x16x32_bf16 v[52:55], v[132:135], v[180:183], v[52:55]
	v_mfma_f32_16x16x32_bf16 v[116:119], v[132:135], v[212:215], v[116:119]
	v_mfma_f32_16x16x32_bf16 v[56:59], v[136:139], v[180:183], v[56:59]
	v_mfma_f32_16x16x32_bf16 v[120:123], v[136:139], v[212:215], v[120:123]
	v_mfma_f32_16x16x32_bf16 v[60:63], v[140:143], v[180:183], v[60:63]
	v_mfma_f32_16x16x32_bf16 v[124:127], v[140:143], v[212:215], v[124:127]
	s_waitcnt lgkmcnt(0)
	v_mfma_f32_16x16x32_bf16 v[0:3], v[148:151], v[184:187], v[0:3]
	v_mfma_f32_16x16x32_bf16 v[64:67], v[148:151], v[216:219], v[64:67]
	v_mfma_f32_16x16x32_bf16 v[4:7], v[152:155], v[184:187], v[4:7]
	v_mfma_f32_16x16x32_bf16 v[68:71], v[152:155], v[216:219], v[68:71]
	v_mfma_f32_16x16x32_bf16 v[8:11], v[156:159], v[184:187], v[8:11]
	v_mfma_f32_16x16x32_bf16 v[72:75], v[156:159], v[216:219], v[72:75]
	v_mfma_f32_16x16x32_bf16 v[12:15], v[160:163], v[184:187], v[12:15]
	v_mfma_f32_16x16x32_bf16 v[76:79], v[160:163], v[216:219], v[76:79]
	v_mfma_f32_16x16x32_bf16 v[16:19], v[148:151], v[188:191], v[16:19]
	v_mfma_f32_16x16x32_bf16 v[80:83], v[148:151], v[220:223], v[80:83]
	v_mfma_f32_16x16x32_bf16 v[20:23], v[152:155], v[188:191], v[20:23]
	v_mfma_f32_16x16x32_bf16 v[84:87], v[152:155], v[220:223], v[84:87]
	v_mfma_f32_16x16x32_bf16 v[24:27], v[156:159], v[188:191], v[24:27]
	v_mfma_f32_16x16x32_bf16 v[88:91], v[156:159], v[220:223], v[88:91]
	v_mfma_f32_16x16x32_bf16 v[28:31], v[160:163], v[188:191], v[28:31]
	v_mfma_f32_16x16x32_bf16 v[92:95], v[160:163], v[220:223], v[92:95]
	v_mfma_f32_16x16x32_bf16 v[32:35], v[148:151], v[192:195], v[32:35]
	v_mfma_f32_16x16x32_bf16 v[96:99], v[148:151], v[224:227], v[96:99]
	v_mfma_f32_16x16x32_bf16 v[36:39], v[152:155], v[192:195], v[36:39]
	v_mfma_f32_16x16x32_bf16 v[100:103], v[152:155], v[224:227], v[100:103]
	v_mfma_f32_16x16x32_bf16 v[40:43], v[156:159], v[192:195], v[40:43]
	v_mfma_f32_16x16x32_bf16 v[104:107], v[156:159], v[224:227], v[104:107]
	v_mfma_f32_16x16x32_bf16 v[44:47], v[160:163], v[192:195], v[44:47]
	v_mfma_f32_16x16x32_bf16 v[108:111], v[160:163], v[224:227], v[108:111]
	v_mfma_f32_16x16x32_bf16 v[48:51], v[148:151], v[196:199], v[48:51]
	v_mfma_f32_16x16x32_bf16 v[112:115], v[148:151], v[228:231], v[112:115]
	v_mfma_f32_16x16x32_bf16 v[52:55], v[152:155], v[196:199], v[52:55]
	v_mfma_f32_16x16x32_bf16 v[116:119], v[152:155], v[228:231], v[116:119]
	v_mfma_f32_16x16x32_bf16 v[56:59], v[156:159], v[196:199], v[56:59]
	v_mfma_f32_16x16x32_bf16 v[120:123], v[156:159], v[228:231], v[120:123]
	v_mfma_f32_16x16x32_bf16 v[60:63], v[160:163], v[196:199], v[60:63]
	v_mfma_f32_16x16x32_bf16 v[124:127], v[160:163], v[228:231], v[124:127]
	s_nop 7
	s_nop 3
	s_mov_b32 s98, s50
	s_mov_b32 s99, s97
	v_lshrrev_b32_e32 v246, 1, v168
	v_and_b32_e32 v246, 0x1c0, v246
	v_and_b32_e32 v247, 15, v168
	v_or_b32_e32 v246, v246, v247
	v_lshl_add_u32 v246, s50, 7, v246
	v_lshrrev_b32_e32 v247, 2, v168
	v_and_b32_e32 v247, 12, v247
	v_and_or_b32 v247, v168, 64, v247
	v_lshl_add_u32 v247, s48, 7, v247
	v_lshlrev_b32_e32 v247, 2, v247
	v_lshl_add_u32 v242, v246, 12, v247
	v_add_u32_e32 v243, 0x10000, v242
	v_add_u32_e32 v244, 0x20000, v242
	v_add_u32_e32 v245, 0x30000, v242
	global_load_dwordx4 v[128:131], v242, s[14:15]
	global_load_dwordx4 v[132:135], v242, s[14:15] offset:64
	global_load_dwordx4 v[136:139], v242, s[14:15] offset:128
	global_load_dwordx4 v[140:143], v242, s[14:15] offset:192
	global_load_dwordx4 v[148:151], v243, s[14:15]
	global_load_dwordx4 v[152:155], v243, s[14:15] offset:64
	global_load_dwordx4 v[156:159], v243, s[14:15] offset:128
	global_load_dwordx4 v[160:163], v243, s[14:15] offset:192
	global_load_dwordx4 v[164:167], v244, s[14:15]
	global_load_dwordx4 v[172:175], v244, s[14:15] offset:64
	global_load_dwordx4 v[176:179], v244, s[14:15] offset:128
	global_load_dwordx4 v[180:183], v244, s[14:15] offset:192
	global_load_dwordx4 v[184:187], v245, s[14:15]
	global_load_dwordx4 v[188:191], v245, s[14:15] offset:64
	global_load_dwordx4 v[192:195], v245, s[14:15] offset:128
	global_load_dwordx4 v[196:199], v245, s[14:15] offset:192
	s_waitcnt vmcnt(15)
	v_pk_add_f32 v[0:1], v[0:1], v[128:129]
	v_pk_add_f32 v[2:3], v[2:3], v[130:131]
	global_store_dwordx4 v242, v[0:3], s[10:11]
	s_waitcnt vmcnt(15)
	v_pk_add_f32 v[4:5], v[4:5], v[132:133]
	v_pk_add_f32 v[6:7], v[6:7], v[134:135]
	global_store_dwordx4 v242, v[4:7], s[10:11] offset:64
	s_waitcnt vmcnt(15)
	v_pk_add_f32 v[8:9], v[8:9], v[136:137]
	v_pk_add_f32 v[10:11], v[10:11], v[138:139]
	global_store_dwordx4 v242, v[8:11], s[10:11] offset:128
	s_waitcnt vmcnt(15)
	v_pk_add_f32 v[12:13], v[12:13], v[140:141]
	v_pk_add_f32 v[14:15], v[14:15], v[142:143]
	global_store_dwordx4 v242, v[12:15], s[10:11] offset:192
	s_waitcnt vmcnt(15)
	v_pk_add_f32 v[16:17], v[16:17], v[148:149]
	v_pk_add_f32 v[18:19], v[18:19], v[150:151]
	global_store_dwordx4 v243, v[16:19], s[10:11]
	s_waitcnt vmcnt(15)
	v_pk_add_f32 v[20:21], v[20:21], v[152:153]
	v_pk_add_f32 v[22:23], v[22:23], v[154:155]
	global_store_dwordx4 v243, v[20:23], s[10:11] offset:64
	s_waitcnt vmcnt(15)
	v_pk_add_f32 v[24:25], v[24:25], v[156:157]
	v_pk_add_f32 v[26:27], v[26:27], v[158:159]
	global_store_dwordx4 v243, v[24:27], s[10:11] offset:128
	s_waitcnt vmcnt(15)
	v_pk_add_f32 v[28:29], v[28:29], v[160:161]
	v_pk_add_f32 v[30:31], v[30:31], v[162:163]
	global_store_dwordx4 v243, v[28:31], s[10:11] offset:192
	s_waitcnt vmcnt(15)
	v_pk_add_f32 v[32:33], v[32:33], v[164:165]
	v_pk_add_f32 v[34:35], v[34:35], v[166:167]
	global_store_dwordx4 v244, v[32:35], s[10:11]
	s_waitcnt vmcnt(15)
	v_pk_add_f32 v[36:37], v[36:37], v[172:173]
	v_pk_add_f32 v[38:39], v[38:39], v[174:175]
	global_store_dwordx4 v244, v[36:39], s[10:11] offset:64
	s_waitcnt vmcnt(15)
	v_pk_add_f32 v[40:41], v[40:41], v[176:177]
	v_pk_add_f32 v[42:43], v[42:43], v[178:179]
	global_store_dwordx4 v244, v[40:43], s[10:11] offset:128
	s_waitcnt vmcnt(15)
	v_pk_add_f32 v[44:45], v[44:45], v[180:181]
	v_pk_add_f32 v[46:47], v[46:47], v[182:183]
	global_store_dwordx4 v244, v[44:47], s[10:11] offset:192
	s_waitcnt vmcnt(15)
	v_pk_add_f32 v[48:49], v[48:49], v[184:185]
	v_pk_add_f32 v[50:51], v[50:51], v[186:187]
	global_store_dwordx4 v245, v[48:51], s[10:11]
	s_waitcnt vmcnt(15)
	v_pk_add_f32 v[52:53], v[52:53], v[188:189]
	v_pk_add_f32 v[54:55], v[54:55], v[190:191]
	global_store_dwordx4 v245, v[52:55], s[10:11] offset:64
	s_waitcnt vmcnt(15)
	v_pk_add_f32 v[56:57], v[56:57], v[192:193]
	v_pk_add_f32 v[58:59], v[58:59], v[194:195]
	global_store_dwordx4 v245, v[56:59], s[10:11] offset:128
	s_waitcnt vmcnt(15)
	v_pk_add_f32 v[60:61], v[60:61], v[196:197]
	v_pk_add_f32 v[62:63], v[62:63], v[198:199]
	global_store_dwordx4 v245, v[60:63], s[10:11] offset:192
	s_add_i32 s61, s61, s60
	s_cmp_eq_u32 s95, 1
	s_cbranch_scc0 .Lgp7_single
	v_lshrrev_b32_e32 v246, 1, v168
	v_and_b32_e32 v246, 0x1c0, v246
	v_and_b32_e32 v247, 15, v168
	v_or_b32_e32 v246, v246, v247
	v_lshl_add_u32 v246, s97, 7, v246
	v_lshrrev_b32_e32 v247, 2, v168
	v_and_b32_e32 v247, 12, v247
	v_and_or_b32 v247, v168, 64, v247
	v_lshl_add_u32 v247, s48, 7, v247
	v_lshlrev_b32_e32 v247, 2, v247
	v_lshl_add_u32 v242, v246, 12, v247
	v_add_u32_e32 v243, 0x10000, v242
	v_add_u32_e32 v244, 0x20000, v242
	v_add_u32_e32 v245, 0x30000, v242
	global_load_dwordx4 v[128:131], v242, s[14:15]
	global_load_dwordx4 v[132:135], v242, s[14:15] offset:64
	global_load_dwordx4 v[136:139], v242, s[14:15] offset:128
	global_load_dwordx4 v[140:143], v242, s[14:15] offset:192
	global_load_dwordx4 v[148:151], v243, s[14:15]
	global_load_dwordx4 v[152:155], v243, s[14:15] offset:64
	global_load_dwordx4 v[156:159], v243, s[14:15] offset:128
	global_load_dwordx4 v[160:163], v243, s[14:15] offset:192
	global_load_dwordx4 v[164:167], v244, s[14:15]
	global_load_dwordx4 v[172:175], v244, s[14:15] offset:64
	global_load_dwordx4 v[176:179], v244, s[14:15] offset:128
	global_load_dwordx4 v[180:183], v244, s[14:15] offset:192
	global_load_dwordx4 v[184:187], v245, s[14:15]
	global_load_dwordx4 v[188:191], v245, s[14:15] offset:64
	global_load_dwordx4 v[192:195], v245, s[14:15] offset:128
	global_load_dwordx4 v[196:199], v245, s[14:15] offset:192
	s_waitcnt vmcnt(15)
	v_pk_add_f32 v[64:65], v[64:65], v[128:129]
	v_pk_add_f32 v[66:67], v[66:67], v[130:131]
	global_store_dwordx4 v242, v[64:67], s[10:11]
	s_waitcnt vmcnt(15)
	v_pk_add_f32 v[68:69], v[68:69], v[132:133]
	v_pk_add_f32 v[70:71], v[70:71], v[134:135]
	global_store_dwordx4 v242, v[68:71], s[10:11] offset:64
	s_waitcnt vmcnt(15)
	v_pk_add_f32 v[72:73], v[72:73], v[136:137]
	v_pk_add_f32 v[74:75], v[74:75], v[138:139]
	global_store_dwordx4 v242, v[72:75], s[10:11] offset:128
	s_waitcnt vmcnt(15)
	v_pk_add_f32 v[76:77], v[76:77], v[140:141]
	v_pk_add_f32 v[78:79], v[78:79], v[142:143]
	global_store_dwordx4 v242, v[76:79], s[10:11] offset:192
	s_waitcnt vmcnt(15)
	v_pk_add_f32 v[80:81], v[80:81], v[148:149]
	v_pk_add_f32 v[82:83], v[82:83], v[150:151]
	global_store_dwordx4 v243, v[80:83], s[10:11]
	s_waitcnt vmcnt(15)
	v_pk_add_f32 v[84:85], v[84:85], v[152:153]
	v_pk_add_f32 v[86:87], v[86:87], v[154:155]
	global_store_dwordx4 v243, v[84:87], s[10:11] offset:64
	s_waitcnt vmcnt(15)
	v_pk_add_f32 v[88:89], v[88:89], v[156:157]
	v_pk_add_f32 v[90:91], v[90:91], v[158:159]
	global_store_dwordx4 v243, v[88:91], s[10:11] offset:128
	s_waitcnt vmcnt(15)
	v_pk_add_f32 v[92:93], v[92:93], v[160:161]
	v_pk_add_f32 v[94:95], v[94:95], v[162:163]
	global_store_dwordx4 v243, v[92:95], s[10:11] offset:192
	s_waitcnt vmcnt(15)
	v_pk_add_f32 v[96:97], v[96:97], v[164:165]
	v_pk_add_f32 v[98:99], v[98:99], v[166:167]
	global_store_dwordx4 v244, v[96:99], s[10:11]
	s_waitcnt vmcnt(15)
	v_pk_add_f32 v[100:101], v[100:101], v[172:173]
	v_pk_add_f32 v[102:103], v[102:103], v[174:175]
	global_store_dwordx4 v244, v[100:103], s[10:11] offset:64
	s_waitcnt vmcnt(15)
	v_pk_add_f32 v[104:105], v[104:105], v[176:177]
	v_pk_add_f32 v[106:107], v[106:107], v[178:179]
	global_store_dwordx4 v244, v[104:107], s[10:11] offset:128
	s_waitcnt vmcnt(15)
	v_pk_add_f32 v[108:109], v[108:109], v[180:181]
	v_pk_add_f32 v[110:111], v[110:111], v[182:183]
	global_store_dwordx4 v244, v[108:111], s[10:11] offset:192
	s_waitcnt vmcnt(15)
	v_pk_add_f32 v[112:113], v[112:113], v[184:185]
	v_pk_add_f32 v[114:115], v[114:115], v[186:187]
	global_store_dwordx4 v245, v[112:115], s[10:11]
	s_waitcnt vmcnt(15)
	v_pk_add_f32 v[116:117], v[116:117], v[188:189]
	v_pk_add_f32 v[118:119], v[118:119], v[190:191]
	global_store_dwordx4 v245, v[116:119], s[10:11] offset:64
	s_waitcnt vmcnt(15)
	v_pk_add_f32 v[120:121], v[120:121], v[192:193]
	v_pk_add_f32 v[122:123], v[122:123], v[194:195]
	global_store_dwordx4 v245, v[120:123], s[10:11] offset:128
	s_waitcnt vmcnt(15)
	v_pk_add_f32 v[124:125], v[124:125], v[196:197]
	v_pk_add_f32 v[126:127], v[126:127], v[198:199]
	global_store_dwordx4 v245, v[124:127], s[10:11] offset:192
	s_add_i32 s61, s61, s60
